# odd-layer in-proj f_logit epilogue: software log1pf expansion replaced by v_log_f32-based log1p with e/(u-1) correction (f32), on top of v2
# speedup vs baseline: 1.0069x; 1.0069x over previous
; #define GAS __attribute__((address_space(1)))
; template <int NP>
; __device__ __forceinline__ void rows_rstd(const float* ssq, float invn, const Unit& u, int wr, int fr, int fq, float (&rs)[2][4]) {
; #pragma unroll
;   for (int ai = 0; ai < 2; ++ai)
; #pragma unroll
;     for (int m = 0; m < 4; ++m) {
;       const int row = erow(u, ai, wr, m, fr);
;       float s;
;       if (NP == 16) {
;         const f32x4 v = *(GAS const f32x4*)(ssq + (size_t)row * 16 + 4 * fq);
;         s = (v[0] + v[1]) + (v[2] + v[3]);
;         s += __shfl_xor(s, 16); s += __shfl_xor(s, 32);
;       } else {
;         const f32x4 v = *(GAS const f32x4*)(ssq + (size_t)row * 4);
;         s = (v[0] + v[1]) + (v[2] + v[3]);
;       }
;       rs[ai][m] = rsqrtf(s * invn + RMS_EPS);
;     }
;   __device__ __forceinline__ void operator()(ACC_T, const Unit& u, int wr, int wc, int fr, int fq) const {
;     if (u.pn == 12 && wc != 0) return;
;     const Params& P = kparams();
;     const float *ssq = P.ssqA, *bfp = P.od_bf; bf16_t *Qc = P.Qc, *Kc = P.Kc, *Vtc = P.Vtc; float* logf = P.logf;
;     float rs[2][4]; rows_rstd<16>(ssq, 1.0f / DM, u, wr, fr, fq, rs);
.LBB0_1426:
	s_cmp_eq_u32 s22, 12
	s_cselect_b64 s[10:11], -1, 0
	s_and_b64 s[10:11], s[34:35], s[10:11]
	s_and_b64 vcc, exec, s[10:11]
	s_cbranch_vccnz .LBB0_1508
	s_mov_b64 s[10:11], s[0:1]
	s_lshl_b32 s80, s12, 8
	v_mov_b64_e32 v[174:175], s[10:11]
	flat_load_dwordx2 v[128:129], v[174:175] offset:232
	s_add_i32 s80, s80, s68
	v_or_b32_e32 v204, s80, v155
	v_or_b32_e32 v196, 16, v204
	v_add_u32_e32 v130, 0x80, v204
	v_mov_b32_e32 v165, v153
	v_ashrrev_i32_e32 v197, 31, v196
	v_ashrrev_i32_e32 v131, 31, v130
	v_or_b32_e32 v192, 32, v204
	v_add_u32_e32 v176, 0x90, v204
	v_lshlrev_b64 v[202:203], 6, v[196:197]
	v_lshlrev_b64 v[130:131], 6, v[130:131]
	v_ashrrev_i32_e32 v193, 31, v192
	v_ashrrev_i32_e32 v177, 31, v176
	flat_load_dwordx2 v[132:133], v[174:175] offset:264
	flat_load_dwordx2 v[134:135], v[174:175] offset:160
	v_or_b32_e32 v184, 48, v204
	v_add_u32_e32 v178, 0xa0, v204
	v_lshlrev_b64 v[194:195], 6, v[192:193]
	v_ashrrev_i32_e32 v205, 31, v204
	v_ashrrev_i32_e32 v185, 31, v184
	v_ashrrev_i32_e32 v179, 31, v178
	v_add_u32_e32 v206, 0xb0, v204
	v_lshlrev_b64 v[208:209], 6, v[204:205]
	v_lshlrev_b64 v[190:191], 6, v[184:185]
	v_ashrrev_i32_e32 v207, 31, v206
	v_lshlrev_b32_e32 v152, 2, v154
	s_cmp_gt_i32 s22, 7
	s_cselect_b64 s[16:17], -1, 0
	s_cmp_gt_u32 s22, 11
	s_cselect_b64 s[60:61], -1, 0
	s_lshl_b32 s97, s22, 8
	s_add_i32 s97, s97, s73
	s_cmp_lt_i32 s22, 4
	v_mov_b32_e32 v167, v153
	s_cselect_b64 s[10:11], -1, 0
	s_ashr_i32 s12, s80, 8
	s_mov_b64 s[62:63], -1
	s_and_b32 s51, s12, -16
	s_waitcnt vmcnt(0) lgkmcnt(0)
	v_lshl_add_u64 v[128:129], v[128:129], 0, v[164:165]
	v_lshl_add_u64 v[180:181], v[128:129], 0, v[202:203]
	v_lshl_add_u64 v[130:131], v[128:129], 0, v[130:131]
	global_load_dwordx4 v[180:183], v[180:181], off
	v_lshl_add_u64 v[186:187], v[128:129], 0, v[194:195]
	global_load_dwordx4 v[220:223], v[130:131], off
	v_lshlrev_b64 v[130:131], 6, v[176:177]
	v_lshl_add_u64 v[130:131], v[128:129], 0, v[130:131]
	global_load_dwordx4 v[186:189], v[186:187], off
	v_lshl_add_u64 v[136:137], v[128:129], 0, v[208:209]
	global_load_dwordx4 v[224:227], v[130:131], off
	v_lshlrev_b64 v[130:131], 6, v[178:179]
	v_lshl_add_u64 v[198:199], v[128:129], 0, v[190:191]
	v_lshl_add_u64 v[130:131], v[128:129], 0, v[130:131]
	global_load_dwordx4 v[136:139], v[136:137], off
	v_and_b32_e32 v178, 64, v216
	global_load_dwordx4 v[198:201], v[198:199], off
	v_xor_b32_e32 v165, 16, v216
	global_load_dwordx4 v[228:231], v[130:131], off
	v_lshlrev_b64 v[130:131], 6, v[206:207]
	v_lshl_add_u64 v[128:129], v[128:129], 0, v[130:131]
	global_load_dwordx4 v[232:235], v[128:129], off
	s_nop 0
	flat_load_dwordx4 v[128:131], v[174:175] offset:520
	flat_load_dwordx2 v[176:177], v[174:175] offset:536
	v_add_u32_e32 v174, 64, v178
	v_xor_b32_e32 v179, 32, v216
	v_cmp_lt_i32_e32 vcc, v165, v174
	s_waitcnt vmcnt(0)
	v_mov_b32_e32 v206, v229
	v_cndmask_b32_e32 v165, v216, v165, vcc
	v_cmp_lt_i32_e32 vcc, v179, v174
	v_mov_b32_e32 v207, v230
	v_mov_b32_e32 v229, v231
	v_cndmask_b32_e32 v174, v216, v179, vcc
	v_lshlrev_b32_e32 v214, 2, v174
	v_lshl_add_u64 v[178:179], v[134:135], 0, v[152:153]
	v_lshl_add_u64 v[174:175], v[132:133], 0, v[152:153]
	v_mov_b32_e32 v132, v137
	v_mov_b32_e32 v133, v138
	v_mov_b32_e32 v137, v139
	v_mov_b32_e32 v134, v181
	v_mov_b32_e32 v135, v182
	v_mov_b32_e32 v181, v183
	v_mov_b32_e32 v138, v187
	v_mov_b32_e32 v139, v188
	v_mov_b32_e32 v187, v189
	v_mov_b32_e32 v182, v199
	v_mov_b32_e32 v183, v200
	v_mov_b32_e32 v199, v201
	v_mov_b32_e32 v188, v221
	v_mov_b32_e32 v189, v222
	v_mov_b32_e32 v221, v223
	v_mov_b32_e32 v200, v225
	v_mov_b32_e32 v201, v226
	v_mov_b32_e32 v225, v227
	v_pk_add_f32 v[132:133], v[132:133], v[136:137]
	v_pk_add_f32 v[134:135], v[134:135], v[180:181]
	v_mov_b32_e32 v210, v233
	v_mov_b32_e32 v211, v234
	v_mov_b32_e32 v233, v235
	v_pk_add_f32 v[136:137], v[138:139], v[186:187]
	v_pk_add_f32 v[138:139], v[182:183], v[198:199]
	v_pk_add_f32 v[180:181], v[188:189], v[220:221]
	v_pk_add_f32 v[182:183], v[200:201], v[224:225]
	v_mov_b32_e32 v198, v134
	v_mov_b32_e32 v199, v132
	v_mov_b32_e32 v132, v135
	v_lshlrev_b32_e32 v165, 2, v165
	v_pk_add_f32 v[186:187], v[206:207], v[228:229]
	v_pk_add_f32 v[188:189], v[210:211], v[232:233]
	v_mov_b32_e32 v134, v138
	v_mov_b32_e32 v135, v136
	v_mov_b32_e32 v136, v139
	v_mov_b32_e32 v138, v182
	v_mov_b32_e32 v139, v180
	v_mov_b32_e32 v180, v183
	v_pk_add_f32 v[132:133], v[198:199], v[132:133]
	v_mov_b32_e32 v182, v188
	v_mov_b32_e32 v183, v186
	v_mov_b32_e32 v186, v189
	v_pk_add_f32 v[134:135], v[134:135], v[136:137]
	v_pk_add_f32 v[136:137], v[138:139], v[180:181]
	ds_bpermute_b32 v181, v165, v133
	ds_bpermute_b32 v180, v165, v132
	v_pk_add_f32 v[138:139], v[182:183], v[186:187]
	ds_bpermute_b32 v183, v165, v135
	ds_bpermute_b32 v182, v165, v134
	ds_bpermute_b32 v187, v165, v137
	s_waitcnt lgkmcnt(0)
	v_pk_add_f32 v[132:133], v[132:133], v[180:181]
	ds_bpermute_b32 v186, v165, v136
	ds_bpermute_b32 v189, v165, v139
	v_pk_add_f32 v[198:199], v[134:135], v[182:183]
	ds_bpermute_b32 v135, v214, v133
	ds_bpermute_b32 v134, v214, v132
	ds_bpermute_b32 v188, v165, v138
	s_waitcnt lgkmcnt(4)
	v_pk_add_f32 v[186:187], v[136:137], v[186:187]
	ds_bpermute_b32 v201, v214, v199
	ds_bpermute_b32 v200, v214, v198
	s_waitcnt lgkmcnt(3)
	v_pk_add_f32 v[132:133], v[132:133], v[134:135]
	s_waitcnt lgkmcnt(2)
	v_pk_add_f32 v[180:181], v[138:139], v[188:189]
	v_pk_fma_f32 v[206:207], v[132:133], s[46:47], v[168:169] op_sel_hi:[1,0,0]
	ds_bpermute_b32 v189, v214, v187
	v_mul_f32_e32 v132, 0x4b800000, v207
	v_cmp_gt_f32_e64 s[14:15], s85, v207
	ds_bpermute_b32 v188, v214, v186
	ds_bpermute_b32 v183, v214, v181
	v_cndmask_b32_e64 v132, v207, v132, s[14:15]
	v_rsq_f32_e32 v132, v132
	ds_bpermute_b32 v182, v214, v180
	s_and_b64 vcc, exec, s[16:17]
	v_lshl_add_u64 v[176:177], v[176:177], 0, v[166:167]
	v_mul_f32_e32 v133, 0x45800000, v132
	v_cmp_gt_f32_e64 s[12:13], s85, v206
	v_cndmask_b32_e64 v165, v132, v133, s[14:15]
	s_cbranch_vccz .LBB0_1435
; #define GAS __attribute__((address_space(1)))
;   __device__ __forceinline__ void operator()(ACC_T, const Unit& u, int wr, int wc, int fr, int fq) const {
;     ...
;         } else if (fq < 2) {
;           f32x4 o0, o1;
;           const f32x4 b0 = *(GAS const f32x4*)(bfp + 8 * fq), b1 = *(GAS const f32x4*)(bfp + 8 * fq + 4);
; #pragma unroll
;           for (int j = 0; j < 4; ++j) {
;             const float x0 = acc[ai][0][m][0][j] * r + b0[j], x1 = acc[ai][0][m][1][j] * r + b1[j];
;             o0[j] = fminf(x0, 0.f) - log1pf(__expf(-fabsf(x0)));
;             o1[j] = fminf(x1, 0.f) - log1pf(__expf(-fabsf(x1)));
;           }
;           *(GAS f32x4*)(logf + (size_t)row * 16 + 8 * fq) = o0; *(GAS f32x4*)(logf + (size_t)row * 16 + 8 * fq + 4) = o1;
	s_mov_b64 s[14:15], -1
	s_and_b64 vcc, exec, s[60:61]
	s_cbranch_vccz .LBB0_1432
	s_and_saveexec_b64 s[14:15], s[6:7]
	s_cbranch_execz .LBB0_1431
	global_load_dwordx4 v[136:139], v[178:179], off
	global_load_dwordx4 v[132:135], v[178:179], off offset:16
	s_waitcnt vmcnt(0)
	v_fma_f32 v152, v124, v165, v136
	v_fma_f32 v167, v125, v165, v137
	v_fma_f32 v207, v126, v165, v138
	v_fma_f32 v210, v127, v165, v139
	v_mul_f32_e64 v211, |v152|, s86
	v_mul_f32_e64 v214, |v167|, s86
	v_mul_f32_e64 v215, |v207|, s86
	v_mul_f32_e64 v220, |v210|, s86
	v_exp_f32_e32 v211, v211
	v_exp_f32_e32 v214, v214
	v_exp_f32_e32 v215, v215
	v_exp_f32_e32 v220, v220
	v_min_f32_e32 v136, 0, v152
	v_min_f32_e32 v137, 0, v167
	v_min_f32_e32 v138, 0, v207
	v_min_f32_e32 v139, 0, v210
	v_add_f32_e32 v221, 1.0, v211
	v_add_f32_e32 v222, 1.0, v214
	v_add_f32_e32 v223, 1.0, v215
	v_add_f32_e32 v224, 1.0, v220
	v_log_f32_e32 v225, v221
	v_log_f32_e32 v226, v222
	v_log_f32_e32 v227, v223
	v_log_f32_e32 v228, v224
	v_add_f32_e32 v229, -1.0, v221
	v_add_f32_e32 v230, -1.0, v222
	v_add_f32_e32 v231, -1.0, v223
	v_add_f32_e32 v232, -1.0, v224
	v_rcp_f32_e32 v233, v229
	v_rcp_f32_e32 v234, v230
	v_rcp_f32_e32 v235, v231
	v_rcp_f32_e32 v236, v232
	v_sub_f32_e32 v152, v136, v211
	v_sub_f32_e32 v167, v137, v214
	v_sub_f32_e32 v207, v138, v215
	v_sub_f32_e32 v210, v139, v220
	v_mul_f32_e32 v233, v211, v233
	v_mul_f32_e32 v234, v214, v234
	v_mul_f32_e32 v235, v215, v235
	v_mul_f32_e32 v236, v220, v236
	v_mul_f32_e32 v225, v225, v233
	v_mul_f32_e32 v226, v226, v234
	v_mul_f32_e32 v227, v227, v235
	v_mul_f32_e32 v228, v228, v236
	v_fmamk_f32 v225, v225, 0xbf317218, v136
	v_fmamk_f32 v226, v226, 0xbf317218, v137
	v_fmamk_f32 v227, v227, 0xbf317218, v138
	v_fmamk_f32 v228, v228, 0xbf317218, v139
	v_cmp_eq_f32_e32 vcc, 0, v229
	s_nop 1
	v_cndmask_b32_e32 v136, v225, v152, vcc
	v_cmp_eq_f32_e32 vcc, 0, v230
	s_nop 1
	v_cndmask_b32_e32 v137, v226, v167, vcc
	v_cmp_eq_f32_e32 vcc, 0, v231
	s_nop 1
	v_cndmask_b32_e32 v138, v227, v207, vcc
	v_cmp_eq_f32_e32 vcc, 0, v232
	s_nop 1
	v_cndmask_b32_e32 v139, v228, v210, vcc
	v_fma_f32 v152, v120, v165, v132
	v_fma_f32 v167, v121, v165, v133
	v_fma_f32 v207, v122, v165, v134
	v_fma_f32 v210, v123, v165, v135
	v_mul_f32_e64 v211, |v152|, s86
	v_mul_f32_e64 v214, |v167|, s86
	v_mul_f32_e64 v215, |v207|, s86
	v_mul_f32_e64 v220, |v210|, s86
	v_exp_f32_e32 v211, v211
	v_exp_f32_e32 v214, v214
	v_exp_f32_e32 v215, v215
	v_exp_f32_e32 v220, v220
	v_min_f32_e32 v132, 0, v152
	v_min_f32_e32 v133, 0, v167
	v_min_f32_e32 v134, 0, v207
	v_min_f32_e32 v135, 0, v210
	v_add_f32_e32 v221, 1.0, v211
	v_add_f32_e32 v222, 1.0, v214
	v_add_f32_e32 v223, 1.0, v215
	v_add_f32_e32 v224, 1.0, v220
	v_log_f32_e32 v225, v221
	v_log_f32_e32 v226, v222
	v_log_f32_e32 v227, v223
	v_log_f32_e32 v228, v224
	v_add_f32_e32 v229, -1.0, v221
	v_add_f32_e32 v230, -1.0, v222
	v_add_f32_e32 v231, -1.0, v223
	v_add_f32_e32 v232, -1.0, v224
	v_rcp_f32_e32 v233, v229
	v_rcp_f32_e32 v234, v230
	v_rcp_f32_e32 v235, v231
	v_rcp_f32_e32 v236, v232
	v_sub_f32_e32 v152, v132, v211
	v_sub_f32_e32 v167, v133, v214
	v_sub_f32_e32 v207, v134, v215
	v_sub_f32_e32 v210, v135, v220
	v_mul_f32_e32 v233, v211, v233
	v_mul_f32_e32 v234, v214, v234
	v_mul_f32_e32 v235, v215, v235
	v_mul_f32_e32 v236, v220, v236
	v_mul_f32_e32 v225, v225, v233
	v_mul_f32_e32 v226, v226, v234
	v_mul_f32_e32 v227, v227, v235
	v_mul_f32_e32 v228, v228, v236
	v_fmamk_f32 v225, v225, 0xbf317218, v132
	v_fmamk_f32 v226, v226, 0xbf317218, v133
	v_fmamk_f32 v227, v227, 0xbf317218, v134
	v_fmamk_f32 v228, v228, 0xbf317218, v135
	v_cmp_eq_f32_e32 vcc, 0, v229
	s_nop 1
	v_cndmask_b32_e32 v132, v225, v152, vcc
	v_cmp_eq_f32_e32 vcc, 0, v230
	s_nop 1
	v_cndmask_b32_e32 v133, v226, v167, vcc
	v_cmp_eq_f32_e32 vcc, 0, v231
	s_nop 1
	v_cndmask_b32_e32 v134, v227, v207, vcc
	v_cmp_eq_f32_e32 vcc, 0, v232
	s_nop 1
	v_cndmask_b32_e32 v135, v228, v210, vcc
	v_lshl_add_u64 v[208:209], v[174:175], 0, v[208:209]
	global_store_dwordx4 v[208:209], v[136:139], off
	global_store_dwordx4 v[208:209], v[132:135], off offset:16

; #define GAS __attribute__((address_space(1)))
; template <int NP>
; __device__ __forceinline__ void rows_rstd(const float* ssq, float invn, const Unit& u, int wr, int fr, int fq, float (&rs)[2][4]) {
;     ...
;         const f32x4 v = *(GAS const f32x4*)(ssq + (size_t)row * 16 + 4 * fq);
;         s = (v[0] + v[1]) + (v[2] + v[3]);
;         s += __shfl_xor(s, 16); s += __shfl_xor(s, 32);
;       } else {
;         const f32x4 v = *(GAS const f32x4*)(ssq + (size_t)row * 4);
;         s = (v[0] + v[1]) + (v[2] + v[3]);
;       }
;       rs[ai][m] = rsqrtf(s * invn + RMS_EPS);
;   __device__ __forceinline__ void operator()(ACC_T, const Unit& u, int wr, int wc, int fr, int fq) const {
;     ...
;         } else if (fq < 2) {
;           f32x4 o0, o1;
;           const f32x4 b0 = *(GAS const f32x4*)(bfp + 8 * fq), b1 = *(GAS const f32x4*)(bfp + 8 * fq + 4);
; #pragma unroll
;           for (int j = 0; j < 4; ++j) {
;             const float x0 = acc[ai][0][m][0][j] * r + b0[j], x1 = acc[ai][0][m][1][j] * r + b1[j];
;             o0[j] = fminf(x0, 0.f) - log1pf(__expf(-fabsf(x0)));
;             o1[j] = fminf(x1, 0.f) - log1pf(__expf(-fabsf(x1)));
;           }
;           *(GAS f32x4*)(logf + (size_t)row * 16 + 8 * fq) = o0; *(GAS f32x4*)(logf + (size_t)row * 16 + 8 * fq + 4) = o1;
.LBB0_1437:
	v_mul_f32_e32 v112, 0x4b800000, v206
	v_cndmask_b32_e64 v112, v206, v112, s[12:13]
	v_rsq_f32_e32 v112, v112
	v_cndmask_b32_e64 v113, 0, 1, s[16:17]
	s_mov_b64 s[62:63], -1
	v_mul_f32_e32 v114, 0x45800000, v112
	v_cndmask_b32_e64 v122, v112, v114, s[12:13]
	v_cndmask_b32_e64 v112, 0, 1, s[60:61]
	v_cmp_ne_u32_e64 s[14:15], 1, v113
	s_andn2_b64 vcc, exec, s[16:17]
	v_cmp_ne_u32_e64 s[12:13], 1, v112
	s_cbranch_vccnz .LBB0_1445
	s_and_b64 vcc, exec, s[12:13]
	s_mov_b64 s[16:17], -1
	s_cbranch_vccnz .LBB0_1442
	s_and_saveexec_b64 s[16:17], s[6:7]
	s_cbranch_execz .LBB0_1441
	global_load_dwordx4 v[116:119], v[178:179], off
	global_load_dwordx4 v[112:115], v[178:179], off offset:16
	s_waitcnt vmcnt(0)
	v_fma_f32 v123, v108, v122, v116
	v_fma_f32 v124, v109, v122, v117
	v_fma_f32 v125, v110, v122, v118
	v_fma_f32 v126, v111, v122, v119
	v_mul_f32_e64 v127, |v123|, s86
	v_mul_f32_e64 v130, |v124|, s86
	v_mul_f32_e64 v131, |v125|, s86
	v_mul_f32_e64 v132, |v126|, s86
	v_exp_f32_e32 v127, v127
	v_exp_f32_e32 v130, v130
	v_exp_f32_e32 v131, v131
	v_exp_f32_e32 v132, v132
	v_min_f32_e32 v116, 0, v123
	v_min_f32_e32 v117, 0, v124
	v_min_f32_e32 v118, 0, v125
	v_min_f32_e32 v119, 0, v126
	v_add_f32_e32 v133, 1.0, v127
	v_add_f32_e32 v134, 1.0, v130
	v_add_f32_e32 v135, 1.0, v131
	v_add_f32_e32 v136, 1.0, v132
	v_log_f32_e32 v137, v133
	v_log_f32_e32 v138, v134
	v_log_f32_e32 v139, v135
	v_log_f32_e32 v152, v136
	v_add_f32_e32 v165, -1.0, v133
	v_add_f32_e32 v167, -1.0, v134
	v_add_f32_e32 v204, -1.0, v135
	v_add_f32_e32 v205, -1.0, v136
	v_rcp_f32_e32 v206, v165
	v_rcp_f32_e32 v207, v167
	v_rcp_f32_e32 v208, v204
	v_rcp_f32_e32 v209, v205
	v_sub_f32_e32 v123, v116, v127
	v_sub_f32_e32 v124, v117, v130
	v_sub_f32_e32 v125, v118, v131
	v_sub_f32_e32 v126, v119, v132
	v_mul_f32_e32 v206, v127, v206
	v_mul_f32_e32 v207, v130, v207
	v_mul_f32_e32 v208, v131, v208
	v_mul_f32_e32 v209, v132, v209
	v_mul_f32_e32 v137, v137, v206
	v_mul_f32_e32 v138, v138, v207
	v_mul_f32_e32 v139, v139, v208
	v_mul_f32_e32 v152, v152, v209
	v_fmamk_f32 v137, v137, 0xbf317218, v116
	v_fmamk_f32 v138, v138, 0xbf317218, v117
	v_fmamk_f32 v139, v139, 0xbf317218, v118
	v_fmamk_f32 v152, v152, 0xbf317218, v119
	v_cmp_eq_f32_e32 vcc, 0, v165
	s_nop 1
	v_cndmask_b32_e32 v116, v137, v123, vcc
	v_cmp_eq_f32_e32 vcc, 0, v167
	s_nop 1
	v_cndmask_b32_e32 v117, v138, v124, vcc
	v_cmp_eq_f32_e32 vcc, 0, v204
	s_nop 1
	v_cndmask_b32_e32 v118, v139, v125, vcc
	v_cmp_eq_f32_e32 vcc, 0, v205
	s_nop 1
	v_cndmask_b32_e32 v119, v152, v126, vcc
	v_fma_f32 v123, v104, v122, v112
	v_fma_f32 v124, v105, v122, v113
	v_fma_f32 v125, v106, v122, v114
	v_fma_f32 v126, v107, v122, v115
	v_mul_f32_e64 v127, |v123|, s86
	v_mul_f32_e64 v130, |v124|, s86
	v_mul_f32_e64 v131, |v125|, s86
	v_mul_f32_e64 v132, |v126|, s86
	v_exp_f32_e32 v127, v127
	v_exp_f32_e32 v130, v130
	v_exp_f32_e32 v131, v131
	v_exp_f32_e32 v132, v132
	v_min_f32_e32 v112, 0, v123
	v_min_f32_e32 v113, 0, v124
	v_min_f32_e32 v114, 0, v125
	v_min_f32_e32 v115, 0, v126
	v_add_f32_e32 v133, 1.0, v127
	v_add_f32_e32 v134, 1.0, v130
	v_add_f32_e32 v135, 1.0, v131
	v_add_f32_e32 v136, 1.0, v132
	v_log_f32_e32 v137, v133
	v_log_f32_e32 v138, v134
	v_log_f32_e32 v139, v135
	v_log_f32_e32 v152, v136
	v_add_f32_e32 v165, -1.0, v133
	v_add_f32_e32 v167, -1.0, v134
	v_add_f32_e32 v204, -1.0, v135
	v_add_f32_e32 v205, -1.0, v136
	v_rcp_f32_e32 v206, v165
	v_rcp_f32_e32 v207, v167
	v_rcp_f32_e32 v208, v204
	v_rcp_f32_e32 v209, v205
	v_sub_f32_e32 v123, v112, v127
	v_sub_f32_e32 v124, v113, v130
	v_sub_f32_e32 v125, v114, v131
	v_sub_f32_e32 v126, v115, v132
	v_mul_f32_e32 v206, v127, v206
	v_mul_f32_e32 v207, v130, v207
	v_mul_f32_e32 v208, v131, v208
	v_mul_f32_e32 v209, v132, v209
	v_mul_f32_e32 v137, v137, v206
	v_mul_f32_e32 v138, v138, v207
	v_mul_f32_e32 v139, v139, v208
	v_mul_f32_e32 v152, v152, v209
	v_fmamk_f32 v137, v137, 0xbf317218, v112
	v_fmamk_f32 v138, v138, 0xbf317218, v113
	v_fmamk_f32 v139, v139, 0xbf317218, v114
	v_fmamk_f32 v152, v152, 0xbf317218, v115
	v_cmp_eq_f32_e32 vcc, 0, v165
	s_nop 1
	v_cndmask_b32_e32 v112, v137, v123, vcc
	v_cmp_eq_f32_e32 vcc, 0, v167
	s_nop 1
	v_cndmask_b32_e32 v113, v138, v124, vcc
	v_cmp_eq_f32_e32 vcc, 0, v204
	s_nop 1
	v_cndmask_b32_e32 v114, v139, v125, vcc
	v_cmp_eq_f32_e32 vcc, 0, v205
	s_nop 1
	v_cndmask_b32_e32 v115, v152, v126, vcc
	v_lshl_add_u64 v[120:121], v[174:175], 0, v[202:203]
	global_store_dwordx4 v[120:121], v[116:119], off
	global_store_dwordx4 v[120:121], v[112:115], off offset:16

; #define GAS __attribute__((address_space(1)))
; template <int NP>
; __device__ __forceinline__ void rows_rstd(const float* ssq, float invn, const Unit& u, int wr, int fr, int fq, float (&rs)[2][4]) {
;     ...
;         const f32x4 v = *(GAS const f32x4*)(ssq + (size_t)row * 16 + 4 * fq);
;         s = (v[0] + v[1]) + (v[2] + v[3]);
;         s += __shfl_xor(s, 16); s += __shfl_xor(s, 32);
;       } else {
;         const f32x4 v = *(GAS const f32x4*)(ssq + (size_t)row * 4);
;         s = (v[0] + v[1]) + (v[2] + v[3]);
;       }
;       rs[ai][m] = rsqrtf(s * invn + RMS_EPS);
;   __device__ __forceinline__ void operator()(ACC_T, const Unit& u, int wr, int wc, int fr, int fq) const {
;     ...
;         } else if (fq < 2) {
;           f32x4 o0, o1;
;           const f32x4 b0 = *(GAS const f32x4*)(bfp + 8 * fq), b1 = *(GAS const f32x4*)(bfp + 8 * fq + 4);
; #pragma unroll
;           for (int j = 0; j < 4; ++j) {
;             const float x0 = acc[ai][0][m][0][j] * r + b0[j], x1 = acc[ai][0][m][1][j] * r + b1[j];
;             o0[j] = fminf(x0, 0.f) - log1pf(__expf(-fabsf(x0)));
;             o1[j] = fminf(x1, 0.f) - log1pf(__expf(-fabsf(x1)));
;           }
;           *(GAS f32x4*)(logf + (size_t)row * 16 + 8 * fq) = o0; *(GAS f32x4*)(logf + (size_t)row * 16 + 8 * fq + 4) = o1;
.LBB0_1447:
	s_waitcnt lgkmcnt(4)
	v_pk_add_f32 v[96:97], v[198:199], v[200:201]
	s_mov_b64 s[60:61], -1
	v_pk_fma_f32 v[104:105], v[96:97], s[46:47], v[168:169] op_sel_hi:[1,0,0]
	s_nop 0
	v_mul_f32_e32 v96, 0x4b800000, v105
	v_cmp_gt_f32_e32 vcc, s85, v105
	v_cmp_gt_f32_e64 s[16:17], s85, v104
	s_nop 0
	v_cndmask_b32_e32 v96, v105, v96, vcc
	v_rsq_f32_e32 v96, v96
	s_nop 0
	v_mul_f32_e32 v97, 0x45800000, v96
	v_cndmask_b32_e32 v105, v96, v97, vcc
	s_and_b64 vcc, exec, s[14:15]
	s_cbranch_vccnz .LBB0_1455
	s_and_b64 vcc, exec, s[12:13]
	s_cbranch_vccnz .LBB0_1452
	s_and_saveexec_b64 s[60:61], s[6:7]
	s_cbranch_execz .LBB0_1451
	global_load_dwordx4 v[100:103], v[178:179], off
	global_load_dwordx4 v[96:99], v[178:179], off offset:16
	s_waitcnt vmcnt(0)
	v_fma_f32 v108, v92, v105, v100
	v_fma_f32 v109, v93, v105, v101
	v_fma_f32 v110, v94, v105, v102
	v_fma_f32 v111, v95, v105, v103
	v_mul_f32_e64 v112, |v108|, s86
	v_mul_f32_e64 v113, |v109|, s86
	v_mul_f32_e64 v114, |v110|, s86
	v_mul_f32_e64 v115, |v111|, s86
	v_exp_f32_e32 v112, v112
	v_exp_f32_e32 v113, v113
	v_exp_f32_e32 v114, v114
	v_exp_f32_e32 v115, v115
	v_min_f32_e32 v100, 0, v108
	v_min_f32_e32 v101, 0, v109
	v_min_f32_e32 v102, 0, v110
	v_min_f32_e32 v103, 0, v111
	v_add_f32_e32 v116, 1.0, v112
	v_add_f32_e32 v117, 1.0, v113
	v_add_f32_e32 v118, 1.0, v114
	v_add_f32_e32 v119, 1.0, v115
	v_log_f32_e32 v120, v116
	v_log_f32_e32 v121, v117
	v_log_f32_e32 v122, v118
	v_log_f32_e32 v123, v119
	v_add_f32_e32 v124, -1.0, v116
	v_add_f32_e32 v125, -1.0, v117
	v_add_f32_e32 v126, -1.0, v118
	v_add_f32_e32 v127, -1.0, v119
	v_rcp_f32_e32 v130, v124
	v_rcp_f32_e32 v131, v125
	v_rcp_f32_e32 v132, v126
	v_rcp_f32_e32 v133, v127
	v_sub_f32_e32 v108, v100, v112
	v_sub_f32_e32 v109, v101, v113
	v_sub_f32_e32 v110, v102, v114
	v_sub_f32_e32 v111, v103, v115
	v_mul_f32_e32 v130, v112, v130
	v_mul_f32_e32 v131, v113, v131
	v_mul_f32_e32 v132, v114, v132
	v_mul_f32_e32 v133, v115, v133
	v_mul_f32_e32 v120, v120, v130
	v_mul_f32_e32 v121, v121, v131
	v_mul_f32_e32 v122, v122, v132
	v_mul_f32_e32 v123, v123, v133
	v_fmamk_f32 v120, v120, 0xbf317218, v100
	v_fmamk_f32 v121, v121, 0xbf317218, v101
	v_fmamk_f32 v122, v122, 0xbf317218, v102
	v_fmamk_f32 v123, v123, 0xbf317218, v103
	v_cmp_eq_f32_e32 vcc, 0, v124
	s_nop 1
	v_cndmask_b32_e32 v100, v120, v108, vcc
	v_cmp_eq_f32_e32 vcc, 0, v125
	s_nop 1
	v_cndmask_b32_e32 v101, v121, v109, vcc
	v_cmp_eq_f32_e32 vcc, 0, v126
	s_nop 1
	v_cndmask_b32_e32 v102, v122, v110, vcc
	v_cmp_eq_f32_e32 vcc, 0, v127
	s_nop 1
	v_cndmask_b32_e32 v103, v123, v111, vcc
	v_fma_f32 v108, v88, v105, v96
	v_fma_f32 v109, v89, v105, v97
	v_fma_f32 v110, v90, v105, v98
	v_fma_f32 v111, v91, v105, v99
	v_mul_f32_e64 v112, |v108|, s86
	v_mul_f32_e64 v113, |v109|, s86
	v_mul_f32_e64 v114, |v110|, s86
	v_mul_f32_e64 v115, |v111|, s86
	v_exp_f32_e32 v112, v112
	v_exp_f32_e32 v113, v113
	v_exp_f32_e32 v114, v114
	v_exp_f32_e32 v115, v115
	v_min_f32_e32 v96, 0, v108
	v_min_f32_e32 v97, 0, v109
	v_min_f32_e32 v98, 0, v110
	v_min_f32_e32 v99, 0, v111
	v_add_f32_e32 v116, 1.0, v112
	v_add_f32_e32 v117, 1.0, v113
	v_add_f32_e32 v118, 1.0, v114
	v_add_f32_e32 v119, 1.0, v115
	v_log_f32_e32 v120, v116
	v_log_f32_e32 v121, v117
	v_log_f32_e32 v122, v118
	v_log_f32_e32 v123, v119
	v_add_f32_e32 v124, -1.0, v116
	v_add_f32_e32 v125, -1.0, v117
	v_add_f32_e32 v126, -1.0, v118
	v_add_f32_e32 v127, -1.0, v119
	v_rcp_f32_e32 v130, v124
	v_rcp_f32_e32 v131, v125
	v_rcp_f32_e32 v132, v126
	v_rcp_f32_e32 v133, v127
	v_sub_f32_e32 v108, v96, v112
	v_sub_f32_e32 v109, v97, v113
	v_sub_f32_e32 v110, v98, v114
	v_sub_f32_e32 v111, v99, v115
	v_mul_f32_e32 v130, v112, v130
	v_mul_f32_e32 v131, v113, v131
	v_mul_f32_e32 v132, v114, v132
	v_mul_f32_e32 v133, v115, v133
	v_mul_f32_e32 v120, v120, v130
	v_mul_f32_e32 v121, v121, v131
	v_mul_f32_e32 v122, v122, v132
	v_mul_f32_e32 v123, v123, v133
	v_fmamk_f32 v120, v120, 0xbf317218, v96
	v_fmamk_f32 v121, v121, 0xbf317218, v97
	v_fmamk_f32 v122, v122, 0xbf317218, v98
	v_fmamk_f32 v123, v123, 0xbf317218, v99
	v_cmp_eq_f32_e32 vcc, 0, v124
	s_nop 1
	v_cndmask_b32_e32 v96, v120, v108, vcc
	v_cmp_eq_f32_e32 vcc, 0, v125
	s_nop 1
	v_cndmask_b32_e32 v97, v121, v109, vcc
	v_cmp_eq_f32_e32 vcc, 0, v126
	s_nop 1
	v_cndmask_b32_e32 v98, v122, v110, vcc
	v_cmp_eq_f32_e32 vcc, 0, v127
	s_nop 1
	v_cndmask_b32_e32 v99, v123, v111, vcc
	v_lshl_add_u64 v[106:107], v[174:175], 0, v[194:195]
	global_store_dwordx4 v[106:107], v[100:103], off
	global_store_dwordx4 v[106:107], v[96:99], off offset:16

; #define GAS __attribute__((address_space(1)))
; template <int NP>
; __device__ __forceinline__ void rows_rstd(const float* ssq, float invn, const Unit& u, int wr, int fr, int fq, float (&rs)[2][4]) {
;     ...
;         const f32x4 v = *(GAS const f32x4*)(ssq + (size_t)row * 16 + 4 * fq);
;         s = (v[0] + v[1]) + (v[2] + v[3]);
;         s += __shfl_xor(s, 16); s += __shfl_xor(s, 32);
;       } else {
;         const f32x4 v = *(GAS const f32x4*)(ssq + (size_t)row * 4);
;         s = (v[0] + v[1]) + (v[2] + v[3]);
;       }
;       rs[ai][m] = rsqrtf(s * invn + RMS_EPS);
;   __device__ __forceinline__ void operator()(ACC_T, const Unit& u, int wr, int wc, int fr, int fq) const {
;     ...
;         } else if (fq < 2) {
;           f32x4 o0, o1;
;           const f32x4 b0 = *(GAS const f32x4*)(bfp + 8 * fq), b1 = *(GAS const f32x4*)(bfp + 8 * fq + 4);
; #pragma unroll
;           for (int j = 0; j < 4; ++j) {
;             const float x0 = acc[ai][0][m][0][j] * r + b0[j], x1 = acc[ai][0][m][1][j] * r + b1[j];
;             o0[j] = fminf(x0, 0.f) - log1pf(__expf(-fabsf(x0)));
;             o1[j] = fminf(x1, 0.f) - log1pf(__expf(-fabsf(x1)));
;           }
;           *(GAS f32x4*)(logf + (size_t)row * 16 + 8 * fq) = o0; *(GAS f32x4*)(logf + (size_t)row * 16 + 8 * fq + 4) = o1;
.LBB0_1457:
	v_mul_f32_e32 v80, 0x4b800000, v104
	v_cndmask_b32_e64 v80, v104, v80, s[16:17]
	v_rsq_f32_e32 v80, v80
	s_and_b64 vcc, exec, s[14:15]
	v_mul_f32_e32 v81, 0x45800000, v80
	v_cndmask_b32_e64 v90, v80, v81, s[16:17]
	s_mov_b64 s[16:17], -1
	s_cbranch_vccnz .LBB0_1465
	s_and_b64 vcc, exec, s[12:13]
	s_cbranch_vccnz .LBB0_1462
	s_and_saveexec_b64 s[16:17], s[6:7]
	s_cbranch_execz .LBB0_1461
	global_load_dwordx4 v[84:87], v[178:179], off
	global_load_dwordx4 v[80:83], v[178:179], off offset:16
	s_waitcnt vmcnt(0)
	v_fma_f32 v91, v76, v90, v84
	v_fma_f32 v92, v77, v90, v85
	v_fma_f32 v93, v78, v90, v86
	v_fma_f32 v94, v79, v90, v87
	v_mul_f32_e64 v95, |v91|, s86
	v_mul_f32_e64 v96, |v92|, s86
	v_mul_f32_e64 v97, |v93|, s86
	v_mul_f32_e64 v98, |v94|, s86
	v_exp_f32_e32 v95, v95
	v_exp_f32_e32 v96, v96
	v_exp_f32_e32 v97, v97
	v_exp_f32_e32 v98, v98
	v_min_f32_e32 v84, 0, v91
	v_min_f32_e32 v85, 0, v92
	v_min_f32_e32 v86, 0, v93
	v_min_f32_e32 v87, 0, v94
	v_add_f32_e32 v99, 1.0, v95
	v_add_f32_e32 v100, 1.0, v96
	v_add_f32_e32 v101, 1.0, v97
	v_add_f32_e32 v102, 1.0, v98
	v_log_f32_e32 v103, v99
	v_log_f32_e32 v104, v100
	v_log_f32_e32 v105, v101
	v_log_f32_e32 v106, v102
	v_add_f32_e32 v107, -1.0, v99
	v_add_f32_e32 v108, -1.0, v100
	v_add_f32_e32 v109, -1.0, v101
	v_add_f32_e32 v110, -1.0, v102
	v_rcp_f32_e32 v111, v107
	v_rcp_f32_e32 v112, v108
	v_rcp_f32_e32 v113, v109
	v_rcp_f32_e32 v114, v110
	v_sub_f32_e32 v91, v84, v95
	v_sub_f32_e32 v92, v85, v96
	v_sub_f32_e32 v93, v86, v97
	v_sub_f32_e32 v94, v87, v98
	v_mul_f32_e32 v111, v95, v111
	v_mul_f32_e32 v112, v96, v112
	v_mul_f32_e32 v113, v97, v113
	v_mul_f32_e32 v114, v98, v114
	v_mul_f32_e32 v103, v103, v111
	v_mul_f32_e32 v104, v104, v112
	v_mul_f32_e32 v105, v105, v113
	v_mul_f32_e32 v106, v106, v114
	v_fmamk_f32 v103, v103, 0xbf317218, v84
	v_fmamk_f32 v104, v104, 0xbf317218, v85
	v_fmamk_f32 v105, v105, 0xbf317218, v86
	v_fmamk_f32 v106, v106, 0xbf317218, v87
	v_cmp_eq_f32_e32 vcc, 0, v107
	s_nop 1
	v_cndmask_b32_e32 v84, v103, v91, vcc
	v_cmp_eq_f32_e32 vcc, 0, v108
	s_nop 1
	v_cndmask_b32_e32 v85, v104, v92, vcc
	v_cmp_eq_f32_e32 vcc, 0, v109
	s_nop 1
	v_cndmask_b32_e32 v86, v105, v93, vcc
	v_cmp_eq_f32_e32 vcc, 0, v110
	s_nop 1
	v_cndmask_b32_e32 v87, v106, v94, vcc
	v_fma_f32 v91, v72, v90, v80
	v_fma_f32 v92, v73, v90, v81
	v_fma_f32 v93, v74, v90, v82
	v_fma_f32 v94, v75, v90, v83
	v_mul_f32_e64 v95, |v91|, s86
	v_mul_f32_e64 v96, |v92|, s86
	v_mul_f32_e64 v97, |v93|, s86
	v_mul_f32_e64 v98, |v94|, s86
	v_exp_f32_e32 v95, v95
	v_exp_f32_e32 v96, v96
	v_exp_f32_e32 v97, v97
	v_exp_f32_e32 v98, v98
	v_min_f32_e32 v80, 0, v91
	v_min_f32_e32 v81, 0, v92
	v_min_f32_e32 v82, 0, v93
	v_min_f32_e32 v83, 0, v94
	v_add_f32_e32 v99, 1.0, v95
	v_add_f32_e32 v100, 1.0, v96
	v_add_f32_e32 v101, 1.0, v97
	v_add_f32_e32 v102, 1.0, v98
	v_log_f32_e32 v103, v99
	v_log_f32_e32 v104, v100
	v_log_f32_e32 v105, v101
	v_log_f32_e32 v106, v102
	v_add_f32_e32 v107, -1.0, v99
	v_add_f32_e32 v108, -1.0, v100
	v_add_f32_e32 v109, -1.0, v101
	v_add_f32_e32 v110, -1.0, v102
	v_rcp_f32_e32 v111, v107
	v_rcp_f32_e32 v112, v108
	v_rcp_f32_e32 v113, v109
	v_rcp_f32_e32 v114, v110
	v_sub_f32_e32 v91, v80, v95
	v_sub_f32_e32 v92, v81, v96
	v_sub_f32_e32 v93, v82, v97
	v_sub_f32_e32 v94, v83, v98
	v_mul_f32_e32 v111, v95, v111
	v_mul_f32_e32 v112, v96, v112
	v_mul_f32_e32 v113, v97, v113
	v_mul_f32_e32 v114, v98, v114
	v_mul_f32_e32 v103, v103, v111
	v_mul_f32_e32 v104, v104, v112
	v_mul_f32_e32 v105, v105, v113
	v_mul_f32_e32 v106, v106, v114
	v_fmamk_f32 v103, v103, 0xbf317218, v80
	v_fmamk_f32 v104, v104, 0xbf317218, v81
	v_fmamk_f32 v105, v105, 0xbf317218, v82
	v_fmamk_f32 v106, v106, 0xbf317218, v83
	v_cmp_eq_f32_e32 vcc, 0, v107
	s_nop 1
	v_cndmask_b32_e32 v80, v103, v91, vcc
	v_cmp_eq_f32_e32 vcc, 0, v108
	s_nop 1
	v_cndmask_b32_e32 v81, v104, v92, vcc
	v_cmp_eq_f32_e32 vcc, 0, v109
	s_nop 1
	v_cndmask_b32_e32 v82, v105, v93, vcc
	v_cmp_eq_f32_e32 vcc, 0, v110
	s_nop 1
	v_cndmask_b32_e32 v83, v106, v94, vcc
	v_lshl_add_u64 v[88:89], v[174:175], 0, v[190:191]
	global_store_dwordx4 v[88:89], v[84:87], off
	global_store_dwordx4 v[88:89], v[80:83], off offset:16

; #define GAS __attribute__((address_space(1)))
; template <int NP>
; __device__ __forceinline__ void rows_rstd(const float* ssq, float invn, const Unit& u, int wr, int fr, int fq, float (&rs)[2][4]) {
;     ...
;         const f32x4 v = *(GAS const f32x4*)(ssq + (size_t)row * 16 + 4 * fq);
;         s = (v[0] + v[1]) + (v[2] + v[3]);
;         s += __shfl_xor(s, 16); s += __shfl_xor(s, 32);
;       } else {
;         const f32x4 v = *(GAS const f32x4*)(ssq + (size_t)row * 4);
;         s = (v[0] + v[1]) + (v[2] + v[3]);
;       }
;       rs[ai][m] = rsqrtf(s * invn + RMS_EPS);
;   __device__ __forceinline__ void operator()(ACC_T, const Unit& u, int wr, int wc, int fr, int fq) const {
;     ...
;         } else if (fq < 2) {
;           f32x4 o0, o1;
;           const f32x4 b0 = *(GAS const f32x4*)(bfp + 8 * fq), b1 = *(GAS const f32x4*)(bfp + 8 * fq + 4);
; #pragma unroll
;           for (int j = 0; j < 4; ++j) {
;             const float x0 = acc[ai][0][m][0][j] * r + b0[j], x1 = acc[ai][0][m][1][j] * r + b1[j];
;             o0[j] = fminf(x0, 0.f) - log1pf(__expf(-fabsf(x0)));
;             o1[j] = fminf(x1, 0.f) - log1pf(__expf(-fabsf(x1)));
;           }
;           *(GAS f32x4*)(logf + (size_t)row * 16 + 8 * fq) = o0; *(GAS f32x4*)(logf + (size_t)row * 16 + 8 * fq + 4) = o1;
.LBB0_1467:
	s_waitcnt lgkmcnt(2)
	v_pk_add_f32 v[64:65], v[186:187], v[188:189]
	s_addk_i32 s80, 0x80
	v_pk_fma_f32 v[74:75], v[64:65], s[46:47], v[168:169] op_sel_hi:[1,0,0]
	s_ashr_i32 s22, s80, 8
	v_mul_f32_e32 v64, 0x4b800000, v75
	v_cmp_gt_f32_e32 vcc, s85, v75
	v_cmp_gt_f32_e64 s[16:17], s85, v74
	v_or_b32_e32 v72, s80, v155
	v_cndmask_b32_e32 v64, v75, v64, vcc
	v_rsq_f32_e32 v64, v64
	s_and_b32 s22, s22, -16
	s_mov_b64 s[60:61], -1
	v_mul_f32_e32 v65, 0x45800000, v64
	v_cndmask_b32_e32 v75, v64, v65, vcc
	s_and_b64 vcc, exec, s[14:15]
	s_cbranch_vccnz .LBB0_1475
	s_and_b64 vcc, exec, s[12:13]
	s_cbranch_vccnz .LBB0_1472
	s_and_saveexec_b64 s[60:61], s[6:7]
	s_cbranch_execz .LBB0_1471
	global_load_dwordx4 v[68:71], v[178:179], off
	global_load_dwordx4 v[64:67], v[178:179], off offset:16
	s_waitcnt vmcnt(0)
	v_fma_f32 v73, v60, v75, v68
	v_fma_f32 v78, v61, v75, v69
	v_fma_f32 v79, v62, v75, v70
	v_fma_f32 v80, v63, v75, v71
	v_mul_f32_e64 v81, |v73|, s86
	v_mul_f32_e64 v82, |v78|, s86
	v_mul_f32_e64 v83, |v79|, s86
	v_mul_f32_e64 v84, |v80|, s86
	v_exp_f32_e32 v81, v81
	v_exp_f32_e32 v82, v82
	v_exp_f32_e32 v83, v83
	v_exp_f32_e32 v84, v84
	v_min_f32_e32 v68, 0, v73
	v_min_f32_e32 v69, 0, v78
	v_min_f32_e32 v70, 0, v79
	v_min_f32_e32 v71, 0, v80
	v_add_f32_e32 v85, 1.0, v81
	v_add_f32_e32 v86, 1.0, v82
	v_add_f32_e32 v87, 1.0, v83
	v_add_f32_e32 v88, 1.0, v84
	v_log_f32_e32 v89, v85
	v_log_f32_e32 v90, v86
	v_log_f32_e32 v91, v87
	v_log_f32_e32 v92, v88
	v_add_f32_e32 v93, -1.0, v85
	v_add_f32_e32 v94, -1.0, v86
	v_add_f32_e32 v95, -1.0, v87
	v_add_f32_e32 v96, -1.0, v88
	v_rcp_f32_e32 v97, v93
	v_rcp_f32_e32 v98, v94
	v_rcp_f32_e32 v99, v95
	v_rcp_f32_e32 v100, v96
	v_sub_f32_e32 v73, v68, v81
	v_sub_f32_e32 v78, v69, v82
	v_sub_f32_e32 v79, v70, v83
	v_sub_f32_e32 v80, v71, v84
	v_mul_f32_e32 v97, v81, v97
	v_mul_f32_e32 v98, v82, v98
	v_mul_f32_e32 v99, v83, v99
	v_mul_f32_e32 v100, v84, v100
	v_mul_f32_e32 v89, v89, v97
	v_mul_f32_e32 v90, v90, v98
	v_mul_f32_e32 v91, v91, v99
	v_mul_f32_e32 v92, v92, v100
	v_fmamk_f32 v89, v89, 0xbf317218, v68
	v_fmamk_f32 v90, v90, 0xbf317218, v69
	v_fmamk_f32 v91, v91, 0xbf317218, v70
	v_fmamk_f32 v92, v92, 0xbf317218, v71
	v_cmp_eq_f32_e32 vcc, 0, v93
	s_nop 1
	v_cndmask_b32_e32 v68, v89, v73, vcc
	v_cmp_eq_f32_e32 vcc, 0, v94
	s_nop 1
	v_cndmask_b32_e32 v69, v90, v78, vcc
	v_cmp_eq_f32_e32 vcc, 0, v95
	s_nop 1
	v_cndmask_b32_e32 v70, v91, v79, vcc
	v_cmp_eq_f32_e32 vcc, 0, v96
	s_nop 1
	v_cndmask_b32_e32 v71, v92, v80, vcc
	v_fma_f32 v73, v56, v75, v64
	v_fma_f32 v78, v57, v75, v65
	v_fma_f32 v79, v58, v75, v66
	v_fma_f32 v80, v59, v75, v67
	v_mul_f32_e64 v81, |v73|, s86
	v_mul_f32_e64 v82, |v78|, s86
	v_mul_f32_e64 v83, |v79|, s86
	v_mul_f32_e64 v84, |v80|, s86
	v_exp_f32_e32 v81, v81
	v_exp_f32_e32 v82, v82
	v_exp_f32_e32 v83, v83
	v_exp_f32_e32 v84, v84
	v_min_f32_e32 v64, 0, v73
	v_min_f32_e32 v65, 0, v78
	v_min_f32_e32 v66, 0, v79
	v_min_f32_e32 v67, 0, v80
	v_add_f32_e32 v85, 1.0, v81
	v_add_f32_e32 v86, 1.0, v82
	v_add_f32_e32 v87, 1.0, v83
	v_add_f32_e32 v88, 1.0, v84
	v_log_f32_e32 v89, v85
	v_log_f32_e32 v90, v86
	v_log_f32_e32 v91, v87
	v_log_f32_e32 v92, v88
	v_add_f32_e32 v93, -1.0, v85
	v_add_f32_e32 v94, -1.0, v86
	v_add_f32_e32 v95, -1.0, v87
	v_add_f32_e32 v96, -1.0, v88
	v_rcp_f32_e32 v97, v93
	v_rcp_f32_e32 v98, v94
	v_rcp_f32_e32 v99, v95
	v_rcp_f32_e32 v100, v96
	v_sub_f32_e32 v73, v64, v81
	v_sub_f32_e32 v78, v65, v82
	v_sub_f32_e32 v79, v66, v83
	v_sub_f32_e32 v80, v67, v84
	v_mul_f32_e32 v97, v81, v97
	v_mul_f32_e32 v98, v82, v98
	v_mul_f32_e32 v99, v83, v99
	v_mul_f32_e32 v100, v84, v100
	v_mul_f32_e32 v89, v89, v97
	v_mul_f32_e32 v90, v90, v98
	v_mul_f32_e32 v91, v91, v99
	v_mul_f32_e32 v92, v92, v100
	v_fmamk_f32 v89, v89, 0xbf317218, v64
	v_fmamk_f32 v90, v90, 0xbf317218, v65
	v_fmamk_f32 v91, v91, 0xbf317218, v66
	v_fmamk_f32 v92, v92, 0xbf317218, v67
	v_cmp_eq_f32_e32 vcc, 0, v93
	s_nop 1
	v_cndmask_b32_e32 v64, v89, v73, vcc
	v_cmp_eq_f32_e32 vcc, 0, v94
	s_nop 1
	v_cndmask_b32_e32 v65, v90, v78, vcc
	v_cmp_eq_f32_e32 vcc, 0, v95
	s_nop 1
	v_cndmask_b32_e32 v66, v91, v79, vcc
	v_cmp_eq_f32_e32 vcc, 0, v96
	s_nop 1
	v_cndmask_b32_e32 v67, v92, v80, vcc
	v_ashrrev_i32_e32 v73, 31, v72
	v_lshlrev_b64 v[76:77], 6, v[72:73]
	v_lshl_add_u64 v[76:77], v[174:175], 0, v[76:77]
	global_store_dwordx4 v[76:77], v[68:71], off
	global_store_dwordx4 v[76:77], v[64:67], off offset:16

; #define GAS __attribute__((address_space(1)))
; template <int NP>
; __device__ __forceinline__ void rows_rstd(const float* ssq, float invn, const Unit& u, int wr, int fr, int fq, float (&rs)[2][4]) {
;     ...
;         const f32x4 v = *(GAS const f32x4*)(ssq + (size_t)row * 16 + 4 * fq);
;         s = (v[0] + v[1]) + (v[2] + v[3]);
;         s += __shfl_xor(s, 16); s += __shfl_xor(s, 32);
;       } else {
;         const f32x4 v = *(GAS const f32x4*)(ssq + (size_t)row * 4);
;         s = (v[0] + v[1]) + (v[2] + v[3]);
;       }
;       rs[ai][m] = rsqrtf(s * invn + RMS_EPS);
;   __device__ __forceinline__ void operator()(ACC_T, const Unit& u, int wr, int wc, int fr, int fq) const {
;     ...
;         } else if (fq < 2) {
;           f32x4 o0, o1;
;           const f32x4 b0 = *(GAS const f32x4*)(bfp + 8 * fq), b1 = *(GAS const f32x4*)(bfp + 8 * fq + 4);
; #pragma unroll
;           for (int j = 0; j < 4; ++j) {
;             const float x0 = acc[ai][0][m][0][j] * r + b0[j], x1 = acc[ai][0][m][1][j] * r + b1[j];
;             o0[j] = fminf(x0, 0.f) - log1pf(__expf(-fabsf(x0)));
;             o1[j] = fminf(x1, 0.f) - log1pf(__expf(-fabsf(x1)));
;           }
;           *(GAS f32x4*)(logf + (size_t)row * 16 + 8 * fq) = o0; *(GAS f32x4*)(logf + (size_t)row * 16 + 8 * fq + 4) = o1;
.LBB0_1477:
	v_mul_f32_e32 v48, 0x4b800000, v74
	v_cndmask_b32_e64 v48, v74, v48, s[16:17]
	v_rsq_f32_e32 v48, v48
	v_or_b32_e32 v56, 16, v72
	s_and_b64 vcc, exec, s[14:15]
	v_mul_f32_e32 v49, 0x45800000, v48
	v_cndmask_b32_e64 v60, v48, v49, s[16:17]
	s_mov_b64 s[16:17], -1
	s_cbranch_vccnz .LBB0_1485
	s_and_b64 vcc, exec, s[12:13]
	s_cbranch_vccnz .LBB0_1482
	s_and_saveexec_b64 s[16:17], s[6:7]
	s_cbranch_execz .LBB0_1481
	global_load_dwordx4 v[52:55], v[178:179], off
	global_load_dwordx4 v[48:51], v[178:179], off offset:16
	s_waitcnt vmcnt(0)
	v_fma_f32 v57, v44, v60, v52
	v_fma_f32 v61, v45, v60, v53
	v_fma_f32 v62, v46, v60, v54
	v_fma_f32 v63, v47, v60, v55
	v_mul_f32_e64 v64, |v57|, s86
	v_mul_f32_e64 v65, |v61|, s86
	v_mul_f32_e64 v66, |v62|, s86
	v_mul_f32_e64 v67, |v63|, s86
	v_exp_f32_e32 v64, v64
	v_exp_f32_e32 v65, v65
	v_exp_f32_e32 v66, v66
	v_exp_f32_e32 v67, v67
	v_min_f32_e32 v52, 0, v57
	v_min_f32_e32 v53, 0, v61
	v_min_f32_e32 v54, 0, v62
	v_min_f32_e32 v55, 0, v63
	v_add_f32_e32 v68, 1.0, v64
	v_add_f32_e32 v69, 1.0, v65
	v_add_f32_e32 v70, 1.0, v66
	v_add_f32_e32 v71, 1.0, v67
	v_log_f32_e32 v73, v68
	v_log_f32_e32 v74, v69
	v_log_f32_e32 v75, v70
	v_log_f32_e32 v76, v71
	v_add_f32_e32 v77, -1.0, v68
	v_add_f32_e32 v78, -1.0, v69
	v_add_f32_e32 v79, -1.0, v70
	v_add_f32_e32 v80, -1.0, v71
	v_rcp_f32_e32 v81, v77
	v_rcp_f32_e32 v82, v78
	v_rcp_f32_e32 v83, v79
	v_rcp_f32_e32 v84, v80
	v_sub_f32_e32 v57, v52, v64
	v_sub_f32_e32 v61, v53, v65
	v_sub_f32_e32 v62, v54, v66
	v_sub_f32_e32 v63, v55, v67
	v_mul_f32_e32 v81, v64, v81
	v_mul_f32_e32 v82, v65, v82
	v_mul_f32_e32 v83, v66, v83
	v_mul_f32_e32 v84, v67, v84
	v_mul_f32_e32 v73, v73, v81
	v_mul_f32_e32 v74, v74, v82
	v_mul_f32_e32 v75, v75, v83
	v_mul_f32_e32 v76, v76, v84
	v_fmamk_f32 v73, v73, 0xbf317218, v52
	v_fmamk_f32 v74, v74, 0xbf317218, v53
	v_fmamk_f32 v75, v75, 0xbf317218, v54
	v_fmamk_f32 v76, v76, 0xbf317218, v55
	v_cmp_eq_f32_e32 vcc, 0, v77
	s_nop 1
	v_cndmask_b32_e32 v52, v73, v57, vcc
	v_cmp_eq_f32_e32 vcc, 0, v78
	s_nop 1
	v_cndmask_b32_e32 v53, v74, v61, vcc
	v_cmp_eq_f32_e32 vcc, 0, v79
	s_nop 1
	v_cndmask_b32_e32 v54, v75, v62, vcc
	v_cmp_eq_f32_e32 vcc, 0, v80
	s_nop 1
	v_cndmask_b32_e32 v55, v76, v63, vcc
	v_fma_f32 v57, v40, v60, v48
	v_fma_f32 v61, v41, v60, v49
	v_fma_f32 v62, v42, v60, v50
	v_fma_f32 v63, v43, v60, v51
	v_mul_f32_e64 v64, |v57|, s86
	v_mul_f32_e64 v65, |v61|, s86
	v_mul_f32_e64 v66, |v62|, s86
	v_mul_f32_e64 v67, |v63|, s86
	v_exp_f32_e32 v64, v64
	v_exp_f32_e32 v65, v65
	v_exp_f32_e32 v66, v66
	v_exp_f32_e32 v67, v67
	v_min_f32_e32 v48, 0, v57
	v_min_f32_e32 v49, 0, v61
	v_min_f32_e32 v50, 0, v62
	v_min_f32_e32 v51, 0, v63
	v_add_f32_e32 v68, 1.0, v64
	v_add_f32_e32 v69, 1.0, v65
	v_add_f32_e32 v70, 1.0, v66
	v_add_f32_e32 v71, 1.0, v67
	v_log_f32_e32 v73, v68
	v_log_f32_e32 v74, v69
	v_log_f32_e32 v75, v70
	v_log_f32_e32 v76, v71
	v_add_f32_e32 v77, -1.0, v68
	v_add_f32_e32 v78, -1.0, v69
	v_add_f32_e32 v79, -1.0, v70
	v_add_f32_e32 v80, -1.0, v71
	v_rcp_f32_e32 v81, v77
	v_rcp_f32_e32 v82, v78
	v_rcp_f32_e32 v83, v79
	v_rcp_f32_e32 v84, v80
	v_sub_f32_e32 v57, v48, v64
	v_sub_f32_e32 v61, v49, v65
	v_sub_f32_e32 v62, v50, v66
	v_sub_f32_e32 v63, v51, v67
	v_mul_f32_e32 v81, v64, v81
	v_mul_f32_e32 v82, v65, v82
	v_mul_f32_e32 v83, v66, v83
	v_mul_f32_e32 v84, v67, v84
	v_mul_f32_e32 v73, v73, v81
	v_mul_f32_e32 v74, v74, v82
	v_mul_f32_e32 v75, v75, v83
	v_mul_f32_e32 v76, v76, v84
	v_fmamk_f32 v73, v73, 0xbf317218, v48
	v_fmamk_f32 v74, v74, 0xbf317218, v49
	v_fmamk_f32 v75, v75, 0xbf317218, v50
	v_fmamk_f32 v76, v76, 0xbf317218, v51
	v_cmp_eq_f32_e32 vcc, 0, v77
	s_nop 1
	v_cndmask_b32_e32 v48, v73, v57, vcc
	v_cmp_eq_f32_e32 vcc, 0, v78
	s_nop 1
	v_cndmask_b32_e32 v49, v74, v61, vcc
	v_cmp_eq_f32_e32 vcc, 0, v79
	s_nop 1
	v_cndmask_b32_e32 v50, v75, v62, vcc
	v_cmp_eq_f32_e32 vcc, 0, v80
	s_nop 1
	v_cndmask_b32_e32 v51, v76, v63, vcc
	v_ashrrev_i32_e32 v57, 31, v56
	v_lshlrev_b64 v[58:59], 6, v[56:57]
	v_lshl_add_u64 v[58:59], v[174:175], 0, v[58:59]
	global_store_dwordx4 v[58:59], v[52:55], off
	global_store_dwordx4 v[58:59], v[48:51], off offset:16

; #define GAS __attribute__((address_space(1)))
; template <int NP>
; __device__ __forceinline__ void rows_rstd(const float* ssq, float invn, const Unit& u, int wr, int fr, int fq, float (&rs)[2][4]) {
;     ...
;         const f32x4 v = *(GAS const f32x4*)(ssq + (size_t)row * 16 + 4 * fq);
;         s = (v[0] + v[1]) + (v[2] + v[3]);
;         s += __shfl_xor(s, 16); s += __shfl_xor(s, 32);
;       } else {
;         const f32x4 v = *(GAS const f32x4*)(ssq + (size_t)row * 4);
;         s = (v[0] + v[1]) + (v[2] + v[3]);
;       }
;       rs[ai][m] = rsqrtf(s * invn + RMS_EPS);
;   __device__ __forceinline__ void operator()(ACC_T, const Unit& u, int wr, int wc, int fr, int fq) const {
;     ...
;         } else if (fq < 2) {
;           f32x4 o0, o1;
;           const f32x4 b0 = *(GAS const f32x4*)(bfp + 8 * fq), b1 = *(GAS const f32x4*)(bfp + 8 * fq + 4);
; #pragma unroll
;           for (int j = 0; j < 4; ++j) {
;             const float x0 = acc[ai][0][m][0][j] * r + b0[j], x1 = acc[ai][0][m][1][j] * r + b1[j];
;             o0[j] = fminf(x0, 0.f) - log1pf(__expf(-fabsf(x0)));
;             o1[j] = fminf(x1, 0.f) - log1pf(__expf(-fabsf(x1)));
;           }
;           *(GAS f32x4*)(logf + (size_t)row * 16 + 8 * fq) = o0; *(GAS f32x4*)(logf + (size_t)row * 16 + 8 * fq + 4) = o1;
.LBB0_1487:
	s_waitcnt lgkmcnt(0)
	v_pk_add_f32 v[32:33], v[180:181], v[182:183]
	v_or_b32_e32 v42, 32, v72
	v_pk_fma_f32 v[40:41], v[32:33], s[46:47], v[168:169] op_sel_hi:[1,0,0]
	s_mov_b64 s[60:61], -1
	v_mul_f32_e32 v32, 0x4b800000, v41
	v_cmp_gt_f32_e32 vcc, s85, v41
	v_cmp_gt_f32_e64 s[16:17], s85, v40
	s_nop 0
	v_cndmask_b32_e32 v32, v41, v32, vcc
	v_rsq_f32_e32 v32, v32
	s_nop 0
	v_mul_f32_e32 v33, 0x45800000, v32
	v_cndmask_b32_e32 v41, v32, v33, vcc
	s_and_b64 vcc, exec, s[14:15]
	s_cbranch_vccnz .LBB0_1495
	s_and_b64 vcc, exec, s[12:13]
	s_cbranch_vccnz .LBB0_1492
	s_and_saveexec_b64 s[60:61], s[6:7]
	s_cbranch_execz .LBB0_1491
	global_load_dwordx4 v[36:39], v[178:179], off
	global_load_dwordx4 v[32:35], v[178:179], off offset:16
	s_waitcnt vmcnt(0)
	v_fma_f32 v43, v28, v41, v36
	v_fma_f32 v46, v29, v41, v37
	v_fma_f32 v47, v30, v41, v38
	v_fma_f32 v48, v31, v41, v39
	v_mul_f32_e64 v49, |v43|, s86
	v_mul_f32_e64 v50, |v46|, s86
	v_mul_f32_e64 v51, |v47|, s86
	v_mul_f32_e64 v52, |v48|, s86
	v_exp_f32_e32 v49, v49
	v_exp_f32_e32 v50, v50
	v_exp_f32_e32 v51, v51
	v_exp_f32_e32 v52, v52
	v_min_f32_e32 v36, 0, v43
	v_min_f32_e32 v37, 0, v46
	v_min_f32_e32 v38, 0, v47
	v_min_f32_e32 v39, 0, v48
	v_add_f32_e32 v53, 1.0, v49
	v_add_f32_e32 v54, 1.0, v50
	v_add_f32_e32 v55, 1.0, v51
	v_add_f32_e32 v56, 1.0, v52
	v_log_f32_e32 v57, v53
	v_log_f32_e32 v58, v54
	v_log_f32_e32 v59, v55
	v_log_f32_e32 v60, v56
	v_add_f32_e32 v61, -1.0, v53
	v_add_f32_e32 v62, -1.0, v54
	v_add_f32_e32 v63, -1.0, v55
	v_add_f32_e32 v64, -1.0, v56
	v_rcp_f32_e32 v65, v61
	v_rcp_f32_e32 v66, v62
	v_rcp_f32_e32 v67, v63
	v_rcp_f32_e32 v68, v64
	v_sub_f32_e32 v43, v36, v49
	v_sub_f32_e32 v46, v37, v50
	v_sub_f32_e32 v47, v38, v51
	v_sub_f32_e32 v48, v39, v52
	v_mul_f32_e32 v65, v49, v65
	v_mul_f32_e32 v66, v50, v66
	v_mul_f32_e32 v67, v51, v67
	v_mul_f32_e32 v68, v52, v68
	v_mul_f32_e32 v57, v57, v65
	v_mul_f32_e32 v58, v58, v66
	v_mul_f32_e32 v59, v59, v67
	v_mul_f32_e32 v60, v60, v68
	v_fmamk_f32 v57, v57, 0xbf317218, v36
	v_fmamk_f32 v58, v58, 0xbf317218, v37
	v_fmamk_f32 v59, v59, 0xbf317218, v38
	v_fmamk_f32 v60, v60, 0xbf317218, v39
	v_cmp_eq_f32_e32 vcc, 0, v61
	s_nop 1
	v_cndmask_b32_e32 v36, v57, v43, vcc
	v_cmp_eq_f32_e32 vcc, 0, v62
	s_nop 1
	v_cndmask_b32_e32 v37, v58, v46, vcc
	v_cmp_eq_f32_e32 vcc, 0, v63
	s_nop 1
	v_cndmask_b32_e32 v38, v59, v47, vcc
	v_cmp_eq_f32_e32 vcc, 0, v64
	s_nop 1
	v_cndmask_b32_e32 v39, v60, v48, vcc
	v_fma_f32 v43, v24, v41, v32
	v_fma_f32 v46, v25, v41, v33
	v_fma_f32 v47, v26, v41, v34
	v_fma_f32 v48, v27, v41, v35
	v_mul_f32_e64 v49, |v43|, s86
	v_mul_f32_e64 v50, |v46|, s86
	v_mul_f32_e64 v51, |v47|, s86
	v_mul_f32_e64 v52, |v48|, s86
	v_exp_f32_e32 v49, v49
	v_exp_f32_e32 v50, v50
	v_exp_f32_e32 v51, v51
	v_exp_f32_e32 v52, v52
	v_min_f32_e32 v32, 0, v43
	v_min_f32_e32 v33, 0, v46
	v_min_f32_e32 v34, 0, v47
	v_min_f32_e32 v35, 0, v48
	v_add_f32_e32 v53, 1.0, v49
	v_add_f32_e32 v54, 1.0, v50
	v_add_f32_e32 v55, 1.0, v51
	v_add_f32_e32 v56, 1.0, v52
	v_log_f32_e32 v57, v53
	v_log_f32_e32 v58, v54
	v_log_f32_e32 v59, v55
	v_log_f32_e32 v60, v56
	v_add_f32_e32 v61, -1.0, v53
	v_add_f32_e32 v62, -1.0, v54
	v_add_f32_e32 v63, -1.0, v55
	v_add_f32_e32 v64, -1.0, v56
	v_rcp_f32_e32 v65, v61
	v_rcp_f32_e32 v66, v62
	v_rcp_f32_e32 v67, v63
	v_rcp_f32_e32 v68, v64
	v_sub_f32_e32 v43, v32, v49
	v_sub_f32_e32 v46, v33, v50
	v_sub_f32_e32 v47, v34, v51
	v_sub_f32_e32 v48, v35, v52
	v_mul_f32_e32 v65, v49, v65
	v_mul_f32_e32 v66, v50, v66
	v_mul_f32_e32 v67, v51, v67
	v_mul_f32_e32 v68, v52, v68
	v_mul_f32_e32 v57, v57, v65
	v_mul_f32_e32 v58, v58, v66
	v_mul_f32_e32 v59, v59, v67
	v_mul_f32_e32 v60, v60, v68
	v_fmamk_f32 v57, v57, 0xbf317218, v32
	v_fmamk_f32 v58, v58, 0xbf317218, v33
	v_fmamk_f32 v59, v59, 0xbf317218, v34
	v_fmamk_f32 v60, v60, 0xbf317218, v35
	v_cmp_eq_f32_e32 vcc, 0, v61
	s_nop 1
	v_cndmask_b32_e32 v32, v57, v43, vcc
	v_cmp_eq_f32_e32 vcc, 0, v62
	s_nop 1
	v_cndmask_b32_e32 v33, v58, v46, vcc
	v_cmp_eq_f32_e32 vcc, 0, v63
	s_nop 1
	v_cndmask_b32_e32 v34, v59, v47, vcc
	v_cmp_eq_f32_e32 vcc, 0, v64
	s_nop 1
	v_cndmask_b32_e32 v35, v60, v48, vcc
	v_ashrrev_i32_e32 v43, 31, v42
	v_lshlrev_b64 v[44:45], 6, v[42:43]
	v_lshl_add_u64 v[44:45], v[174:175], 0, v[44:45]
	global_store_dwordx4 v[44:45], v[36:39], off
	global_store_dwordx4 v[44:45], v[32:35], off offset:16

; #define GAS __attribute__((address_space(1)))
;   __device__ __forceinline__ void operator()(ACC_T, const Unit& u, int wr, int wc, int fr, int fq) const {
;     ...
;         } else if (fq < 2) {
;           f32x4 o0, o1;
;           const f32x4 b0 = *(GAS const f32x4*)(bfp + 8 * fq), b1 = *(GAS const f32x4*)(bfp + 8 * fq + 4);
; #pragma unroll
;           for (int j = 0; j < 4; ++j) {
;             const float x0 = acc[ai][0][m][0][j] * r + b0[j], x1 = acc[ai][0][m][1][j] * r + b1[j];
;             o0[j] = fminf(x0, 0.f) - log1pf(__expf(-fabsf(x0)));
;             o1[j] = fminf(x1, 0.f) - log1pf(__expf(-fabsf(x1)));
;           }
;           *(GAS f32x4*)(logf + (size_t)row * 16 + 8 * fq) = o0; *(GAS f32x4*)(logf + (size_t)row * 16 + 8 * fq + 4) = o1;
.LBB0_1497:
	v_mul_f32_e32 v16, 0x4b800000, v40
	v_cndmask_b32_e64 v16, v40, v16, s[16:17]
	v_rsq_f32_e32 v16, v16
	v_or_b32_e32 v24, 48, v72
	s_and_b64 vcc, exec, s[14:15]
	v_mul_f32_e32 v17, 0x45800000, v16
	v_cndmask_b32_e64 v28, v16, v17, s[16:17]
	s_mov_b64 s[14:15], -1
	s_cbranch_vccnz .LBB0_1505
	s_and_b64 vcc, exec, s[12:13]
	s_mov_b64 s[12:13], -1
	s_cbranch_vccnz .LBB0_1502
	s_and_saveexec_b64 s[12:13], s[6:7]
	s_cbranch_execz .LBB0_1501
	global_load_dwordx4 v[20:23], v[178:179], off
	global_load_dwordx4 v[16:19], v[178:179], off offset:16
	s_waitcnt vmcnt(0)
	v_fma_f32 v25, v12, v28, v20
	v_fma_f32 v29, v13, v28, v21
	v_fma_f32 v30, v14, v28, v22
	v_fma_f32 v31, v15, v28, v23
	v_mul_f32_e64 v32, |v25|, s86
	v_mul_f32_e64 v33, |v29|, s86
	v_mul_f32_e64 v34, |v30|, s86
	v_mul_f32_e64 v35, |v31|, s86
	v_exp_f32_e32 v32, v32
	v_exp_f32_e32 v33, v33
	v_exp_f32_e32 v34, v34
	v_exp_f32_e32 v35, v35
	v_min_f32_e32 v20, 0, v25
	v_min_f32_e32 v21, 0, v29
	v_min_f32_e32 v22, 0, v30
	v_min_f32_e32 v23, 0, v31
	v_add_f32_e32 v36, 1.0, v32
	v_add_f32_e32 v37, 1.0, v33
	v_add_f32_e32 v38, 1.0, v34
	v_add_f32_e32 v39, 1.0, v35
	v_log_f32_e32 v40, v36
	v_log_f32_e32 v41, v37
	v_log_f32_e32 v42, v38
	v_log_f32_e32 v43, v39
	v_add_f32_e32 v44, -1.0, v36
	v_add_f32_e32 v45, -1.0, v37
	v_add_f32_e32 v46, -1.0, v38
	v_add_f32_e32 v47, -1.0, v39
	v_rcp_f32_e32 v48, v44
	v_rcp_f32_e32 v49, v45
	v_rcp_f32_e32 v50, v46
	v_rcp_f32_e32 v51, v47
	v_sub_f32_e32 v25, v20, v32
	v_sub_f32_e32 v29, v21, v33
	v_sub_f32_e32 v30, v22, v34
	v_sub_f32_e32 v31, v23, v35
	v_mul_f32_e32 v48, v32, v48
	v_mul_f32_e32 v49, v33, v49
	v_mul_f32_e32 v50, v34, v50
	v_mul_f32_e32 v51, v35, v51
	v_mul_f32_e32 v40, v40, v48
	v_mul_f32_e32 v41, v41, v49
	v_mul_f32_e32 v42, v42, v50
	v_mul_f32_e32 v43, v43, v51
	v_fmamk_f32 v40, v40, 0xbf317218, v20
	v_fmamk_f32 v41, v41, 0xbf317218, v21
	v_fmamk_f32 v42, v42, 0xbf317218, v22
	v_fmamk_f32 v43, v43, 0xbf317218, v23
	v_cmp_eq_f32_e32 vcc, 0, v44
	s_nop 1
	v_cndmask_b32_e32 v20, v40, v25, vcc
	v_cmp_eq_f32_e32 vcc, 0, v45
	s_nop 1
	v_cndmask_b32_e32 v21, v41, v29, vcc
	v_cmp_eq_f32_e32 vcc, 0, v46
	s_nop 1
	v_cndmask_b32_e32 v22, v42, v30, vcc
	v_cmp_eq_f32_e32 vcc, 0, v47
	s_nop 1
	v_cndmask_b32_e32 v23, v43, v31, vcc
	v_fma_f32 v25, v8, v28, v16
	v_fma_f32 v29, v9, v28, v17
	v_fma_f32 v30, v10, v28, v18
	v_fma_f32 v31, v11, v28, v19
	v_mul_f32_e64 v32, |v25|, s86
	v_mul_f32_e64 v33, |v29|, s86
	v_mul_f32_e64 v34, |v30|, s86
	v_mul_f32_e64 v35, |v31|, s86
	v_exp_f32_e32 v32, v32
	v_exp_f32_e32 v33, v33
	v_exp_f32_e32 v34, v34
	v_exp_f32_e32 v35, v35
	v_min_f32_e32 v16, 0, v25
	v_min_f32_e32 v17, 0, v29
	v_min_f32_e32 v18, 0, v30
	v_min_f32_e32 v19, 0, v31
	v_add_f32_e32 v36, 1.0, v32
	v_add_f32_e32 v37, 1.0, v33
	v_add_f32_e32 v38, 1.0, v34
	v_add_f32_e32 v39, 1.0, v35
	v_log_f32_e32 v40, v36
	v_log_f32_e32 v41, v37
	v_log_f32_e32 v42, v38
	v_log_f32_e32 v43, v39
	v_add_f32_e32 v44, -1.0, v36
	v_add_f32_e32 v45, -1.0, v37
	v_add_f32_e32 v46, -1.0, v38
	v_add_f32_e32 v47, -1.0, v39
	v_rcp_f32_e32 v48, v44
	v_rcp_f32_e32 v49, v45
	v_rcp_f32_e32 v50, v46
	v_rcp_f32_e32 v51, v47
	v_sub_f32_e32 v25, v16, v32
	v_sub_f32_e32 v29, v17, v33
	v_sub_f32_e32 v30, v18, v34
	v_sub_f32_e32 v31, v19, v35
	v_mul_f32_e32 v48, v32, v48
	v_mul_f32_e32 v49, v33, v49
	v_mul_f32_e32 v50, v34, v50
	v_mul_f32_e32 v51, v35, v51
	v_mul_f32_e32 v40, v40, v48
	v_mul_f32_e32 v41, v41, v49
	v_mul_f32_e32 v42, v42, v50
	v_mul_f32_e32 v43, v43, v51
	v_fmamk_f32 v40, v40, 0xbf317218, v16
	v_fmamk_f32 v41, v41, 0xbf317218, v17
	v_fmamk_f32 v42, v42, 0xbf317218, v18
	v_fmamk_f32 v43, v43, 0xbf317218, v19
	v_cmp_eq_f32_e32 vcc, 0, v44
	s_nop 1
	v_cndmask_b32_e32 v16, v40, v25, vcc
	v_cmp_eq_f32_e32 vcc, 0, v45
	s_nop 1
	v_cndmask_b32_e32 v17, v41, v29, vcc
	v_cmp_eq_f32_e32 vcc, 0, v46
	s_nop 1
	v_cndmask_b32_e32 v18, v42, v30, vcc
	v_cmp_eq_f32_e32 vcc, 0, v47
	s_nop 1
	v_cndmask_b32_e32 v19, v43, v31, vcc
	v_ashrrev_i32_e32 v25, 31, v24
	v_lshlrev_b64 v[26:27], 6, v[24:25]
	v_lshl_add_u64 v[26:27], v[174:175], 0, v[26:27]
	global_store_dwordx4 v[26:27], v[20:23], off
	global_store_dwordx4 v[26:27], v[16:19], off offset:16
